# hand-written final RMSNorm loop (4 rows per iteration, loads batched); plus peeled GEMM first iteration, epilogue fast paths, LRU prefetch, sc1 stores
# baseline (speedup 1.0000x reference)
; #define LANE_IDS() int tid_l = threadIdx.x; asm volatile("" : "+v"(tid_l)); const int tid = tid_l, lane = tid & 63, wave = __builtin_amdgcn_readfirstlane(tid >> 6), gw = blockIdx.x * 8 + wave, NGW = gridDim.x * 8; (void)gw; (void)NGW; (void)lane
; __global__ void __launch_bounds__(512, 2) fwd_mega(Args a) {
;     ...
;     {
;         LANE_IDS();
;         const float* ssf = SS + (size_t)12 * M * 16;
;         f32x4 gv[4];
; #pragma unroll
;         for (int j = 0; j < 4; ++j) gv[j] = *((const f32x4*)a.final_norm + lane + 64 * j);
;         for (int row = gw; row < M; row += NGW) {
;             const float rs = row_rstd(ssf, row);
;             f32x4* orow = (f32x4*)(a.out + (size_t)row * D) + lane; const u32x2* xr = (const u32x2*)(XB + (size_t)row * D) + lane;
.LBB0_1139:
	v_readlane_b32 s1, v253, 32
	v_readfirstlane_b32 s0, v252
	s_ashr_i32 s0, s0, 6
	s_add_i32 s0, s0, s1
	s_cmpk_lt_i32 s0, 0x4000
	v_readlane_b32 s16, v253, 50
	v_readlane_b32 s17, v253, 51
	s_cbranch_scc0 .LBB0_1142
	v_readlane_b32 s36, v253, 16
	v_and_b32_e32 v18, 63, v252
	v_readlane_b32 s48, v253, 28
	v_readlane_b32 s49, v253, 29
	v_lshlrev_b32_e32 v16, 4, v18
	v_readlane_b32 s50, v253, 30
	v_readlane_b32 s51, v253, 31
	s_mov_b64 s[12:13], s[48:49]
	global_load_dwordx4 v[0:3], v16, s[12:13]
	global_load_dwordx4 v[4:7], v16, s[12:13] offset:1024
	global_load_dwordx4 v[8:11], v16, s[12:13] offset:2048
	global_load_dwordx4 v[12:15], v16, s[12:13] offset:3072
	s_ashr_i32 s1, s0, 31
	s_lshl_b64 s[2:3], s[0:1], 11
	s_ashr_i32 s17, s16, 31
	s_mov_b64 s[14:15], s[50:51]
	v_lshl_or_b32 v18, v18, 3, s2
	v_mov_b32_e32 v19, s3
	s_lshl_b64 s[2:3], s[16:17], 11
	s_lshl_b64 s[4:5], s[0:1], 6
	s_lshl_b64 s[6:7], s[16:17], 6
	s_lshl_b64 s[8:9], s[0:1], 12
	s_add_u32 s8, s14, s8
	v_mov_b32_e32 v17, 0
	s_addc_u32 s9, s15, s9
	v_lshl_add_u64 v[20:21], s[8:9], 0, v[16:17]
	s_mov_b64 s[8:9], 0xc00
	v_lshl_add_u64 v[20:21], v[20:21], 0, s[8:9]
	s_lshl_b64 s[8:9], s[16:17], 12
	v_mov_b32_e32 v16, 0x18680000
	v_mov_b32_e32 v22, 0x358637bd
	s_mov_b32 s1, 0x800000
	s_mov_b32 s10, 0x6280000
	v_readlane_b32 s37, v253, 17
	v_readlane_b32 s38, v253, 18
	v_readlane_b32 s39, v253, 19
	v_readlane_b32 s40, v253, 20
	v_readlane_b32 s41, v253, 21
	v_readlane_b32 s42, v253, 22
	v_readlane_b32 s43, v253, 23
	v_readlane_b32 s44, v253, 24
	v_readlane_b32 s45, v253, 25
	v_readlane_b32 s46, v253, 26
	v_readlane_b32 s47, v253, 27
	v_and_b32_e32 v40, 63, v252
	v_lshlrev_b32_e32 v41, 4, v40
	v_lshlrev_b32_e32 v40, 3, v40
	v_mov_b32_e32 v17, 0
	v_mov_b32_e32 v22, 0x358637bd
.Lfn_loop:
	s_mov_b32 s20, s0
	s_lshl_b32 s12, s20, 6
	s_add_u32 s12, s64, s12
	s_addc_u32 s13, s65, 0
	s_add_u32 s12, s12, 0x18680000
	s_addc_u32 s13, s13, 0
	global_load_dwordx4 v[48:51], v17, s[12:13]
	global_load_dwordx4 v[52:55], v17, s[12:13] offset:16
	global_load_dwordx4 v[56:59], v17, s[12:13] offset:32
	global_load_dwordx4 v[60:63], v17, s[12:13] offset:48
	s_lshl_b32 s14, s20, 11
	s_add_u32 s14, s64, s14
	s_addc_u32 s15, s65, 0
	s_add_u32 s14, s14, 0x6280000
	s_addc_u32 s15, s15, 0
	global_load_dwordx2 v[64:65], v40, s[14:15]
	global_load_dwordx2 v[66:67], v40, s[14:15] offset:512
	global_load_dwordx2 v[68:69], v40, s[14:15] offset:1024
	global_load_dwordx2 v[70:71], v40, s[14:15] offset:1536
	s_mul_i32 s21, s16, 1
	s_add_i32 s21, s21, s0
	s_cmp_gt_i32 s21, 0x3fff
	s_cselect_b32 s21, s0, s21
	s_lshl_b32 s12, s21, 6
	s_add_u32 s12, s64, s12
	s_addc_u32 s13, s65, 0
	s_add_u32 s12, s12, 0x18680000
	s_addc_u32 s13, s13, 0
	global_load_dwordx4 v[72:75], v17, s[12:13]
	global_load_dwordx4 v[76:79], v17, s[12:13] offset:16
	global_load_dwordx4 v[80:83], v17, s[12:13] offset:32
	global_load_dwordx4 v[84:87], v17, s[12:13] offset:48
	s_lshl_b32 s14, s21, 11
	s_add_u32 s14, s64, s14
	s_addc_u32 s15, s65, 0
	s_add_u32 s14, s14, 0x6280000
	s_addc_u32 s15, s15, 0
	global_load_dwordx2 v[88:89], v40, s[14:15]
	global_load_dwordx2 v[90:91], v40, s[14:15] offset:512
	global_load_dwordx2 v[92:93], v40, s[14:15] offset:1024
	global_load_dwordx2 v[94:95], v40, s[14:15] offset:1536
	s_mul_i32 s22, s16, 2
	s_add_i32 s22, s22, s0
	s_cmp_gt_i32 s22, 0x3fff
	s_cselect_b32 s22, s0, s22
	s_lshl_b32 s12, s22, 6
	s_add_u32 s12, s64, s12
	s_addc_u32 s13, s65, 0
	s_add_u32 s12, s12, 0x18680000
	s_addc_u32 s13, s13, 0
	global_load_dwordx4 v[96:99], v17, s[12:13]
	global_load_dwordx4 v[100:103], v17, s[12:13] offset:16
	global_load_dwordx4 v[104:107], v17, s[12:13] offset:32
	global_load_dwordx4 v[108:111], v17, s[12:13] offset:48
	s_lshl_b32 s14, s22, 11
	s_add_u32 s14, s64, s14
	s_addc_u32 s15, s65, 0
	s_add_u32 s14, s14, 0x6280000
	s_addc_u32 s15, s15, 0
	global_load_dwordx2 v[112:113], v40, s[14:15]
	global_load_dwordx2 v[114:115], v40, s[14:15] offset:512
	global_load_dwordx2 v[116:117], v40, s[14:15] offset:1024
	global_load_dwordx2 v[118:119], v40, s[14:15] offset:1536
	s_mul_i32 s23, s16, 3
	s_add_i32 s23, s23, s0
	s_cmp_gt_i32 s23, 0x3fff
	s_cselect_b32 s23, s0, s23
	s_lshl_b32 s12, s23, 6
	s_add_u32 s12, s64, s12
	s_addc_u32 s13, s65, 0
	s_add_u32 s12, s12, 0x18680000
	s_addc_u32 s13, s13, 0
	global_load_dwordx4 v[120:123], v17, s[12:13]
	global_load_dwordx4 v[124:127], v17, s[12:13] offset:16
	global_load_dwordx4 v[128:131], v17, s[12:13] offset:32
	global_load_dwordx4 v[132:135], v17, s[12:13] offset:48
	s_lshl_b32 s14, s23, 11
	s_add_u32 s14, s64, s14
	s_addc_u32 s15, s65, 0
	s_add_u32 s14, s14, 0x6280000
	s_addc_u32 s15, s15, 0
	global_load_dwordx2 v[136:137], v40, s[14:15]
	global_load_dwordx2 v[138:139], v40, s[14:15] offset:512
	global_load_dwordx2 v[140:141], v40, s[14:15] offset:1024
	global_load_dwordx2 v[142:143], v40, s[14:15] offset:1536
	s_mov_b32 s1, 0x800000
	s_waitcnt vmcnt(24)
; __device__ __forceinline__ float bflo(unsigned w) { return __uint_as_float(w << 16); }
; __device__ __forceinline__ float bfhi(unsigned w) { return __uint_as_float(w & 0xffff0000u); }
; __global__ void __launch_bounds__(512, 2) fwd_mega(Args a) {
;     ...
;         for (int row = gw; row < M; row += NGW) {
;             const float rs = row_rstd(ssf, row);
;             f32x4* orow = (f32x4*)(a.out + (size_t)row * D) + lane; const u32x2* xr = (const u32x2*)(XB + (size_t)row * D) + lane;
; #pragma unroll
;             for (int j = 0; j < 4; ++j) { const u32x2 w = xr[64 * j]; orow[64 * j] = (f32x4){bflo(w.x), bfhi(w.x), bflo(w.y), bfhi(w.y)} * rs * gv[j]; }
	v_pk_add_f32 v[48:49], v[48:49], v[52:53]
	v_pk_add_f32 v[50:51], v[50:51], v[54:55]
	v_pk_add_f32 v[56:57], v[56:57], v[60:61]
	v_pk_add_f32 v[58:59], v[58:59], v[62:63]
	v_pk_add_f32 v[48:49], v[48:49], v[56:57]
	v_pk_add_f32 v[50:51], v[50:51], v[58:59]
	v_add_f32_e32 v48, v48, v49
	v_add_f32_e32 v50, v50, v51
	v_add_f32_e32 v48, v48, v50
	v_fmamk_f32 v48, v48, 0x3a800000, v22
	v_mul_f32_e32 v49, 0x4b800000, v48
	v_cmp_gt_f32_e32 vcc, s1, v48
	s_nop 1
	v_cndmask_b32_e32 v48, v48, v49, vcc
	v_rsq_f32_e32 v48, v48
	s_nop 0
	v_mul_f32_e32 v49, 0x45800000, v48
	v_cndmask_b32_e32 v52, v48, v49, vcc
	s_lshl_b32 s14, s20, 12
	s_add_u32 s14, s50, s14
	s_addc_u32 s15, s51, 0
	v_lshlrev_b32_e32 v48, 16, v64
	v_and_b32_e32 v49, 0xffff0000, v64
	v_lshlrev_b32_e32 v50, 16, v65
	v_and_b32_e32 v51, 0xffff0000, v65
	v_pk_mul_f32 v[48:49], v[52:53], v[48:49] op_sel_hi:[0,1]
	v_pk_mul_f32 v[50:51], v[52:53], v[50:51] op_sel_hi:[0,1]
	v_pk_mul_f32 v[56:57], v[0:1], v[48:49]
	v_pk_mul_f32 v[58:59], v[2:3], v[50:51]
	global_store_dwordx4 v41, v[56:59], s[14:15]
	v_lshlrev_b32_e32 v48, 16, v66
	v_and_b32_e32 v49, 0xffff0000, v66
	v_lshlrev_b32_e32 v50, 16, v67
	v_and_b32_e32 v51, 0xffff0000, v67
	v_pk_mul_f32 v[48:49], v[52:53], v[48:49] op_sel_hi:[0,1]
	v_pk_mul_f32 v[50:51], v[52:53], v[50:51] op_sel_hi:[0,1]
	v_pk_mul_f32 v[60:61], v[4:5], v[48:49]
	v_pk_mul_f32 v[62:63], v[6:7], v[50:51]
	global_store_dwordx4 v41, v[60:63], s[14:15] offset:1024
	s_nop 0
	v_lshlrev_b32_e32 v48, 16, v68
	v_and_b32_e32 v49, 0xffff0000, v68
	v_lshlrev_b32_e32 v50, 16, v69
	v_and_b32_e32 v51, 0xffff0000, v69
	v_pk_mul_f32 v[48:49], v[52:53], v[48:49] op_sel_hi:[0,1]
	v_pk_mul_f32 v[50:51], v[52:53], v[50:51] op_sel_hi:[0,1]
	v_pk_mul_f32 v[56:57], v[8:9], v[48:49]
	v_pk_mul_f32 v[58:59], v[10:11], v[50:51]
	global_store_dwordx4 v41, v[56:59], s[14:15] offset:2048
	s_nop 0
	v_lshlrev_b32_e32 v48, 16, v70
	v_and_b32_e32 v49, 0xffff0000, v70
	v_lshlrev_b32_e32 v50, 16, v71
	v_and_b32_e32 v51, 0xffff0000, v71
	v_pk_mul_f32 v[48:49], v[52:53], v[48:49] op_sel_hi:[0,1]
	v_pk_mul_f32 v[50:51], v[52:53], v[50:51] op_sel_hi:[0,1]
	v_pk_mul_f32 v[60:61], v[12:13], v[48:49]
	v_pk_mul_f32 v[62:63], v[14:15], v[50:51]
	global_store_dwordx4 v41, v[60:63], s[14:15] offset:3072
	s_nop 0
	s_waitcnt vmcnt(20)
	v_pk_add_f32 v[72:73], v[72:73], v[76:77]
	v_pk_add_f32 v[74:75], v[74:75], v[78:79]
	v_pk_add_f32 v[80:81], v[80:81], v[84:85]
	v_pk_add_f32 v[82:83], v[82:83], v[86:87]
	v_pk_add_f32 v[72:73], v[72:73], v[80:81]
	v_pk_add_f32 v[74:75], v[74:75], v[82:83]
	v_add_f32_e32 v72, v72, v73
	v_add_f32_e32 v74, v74, v75
	v_add_f32_e32 v72, v72, v74
	v_fmamk_f32 v72, v72, 0x3a800000, v22
	v_mul_f32_e32 v73, 0x4b800000, v72
	v_cmp_gt_f32_e32 vcc, s1, v72
	s_nop 1
	v_cndmask_b32_e32 v72, v72, v73, vcc
	v_rsq_f32_e32 v72, v72
	s_nop 0
	v_mul_f32_e32 v73, 0x45800000, v72
	v_cndmask_b32_e32 v76, v72, v73, vcc
	s_lshl_b32 s14, s21, 12
	s_add_u32 s14, s50, s14
	s_addc_u32 s15, s51, 0
	v_lshlrev_b32_e32 v72, 16, v88
	v_and_b32_e32 v73, 0xffff0000, v88
	v_lshlrev_b32_e32 v74, 16, v89
	v_and_b32_e32 v75, 0xffff0000, v89
	v_pk_mul_f32 v[72:73], v[76:77], v[72:73] op_sel_hi:[0,1]
	v_pk_mul_f32 v[74:75], v[76:77], v[74:75] op_sel_hi:[0,1]
	v_pk_mul_f32 v[80:81], v[0:1], v[72:73]
	v_pk_mul_f32 v[82:83], v[2:3], v[74:75]
	global_store_dwordx4 v41, v[80:83], s[14:15]
	v_lshlrev_b32_e32 v72, 16, v90
	v_and_b32_e32 v73, 0xffff0000, v90
	v_lshlrev_b32_e32 v74, 16, v91
	v_and_b32_e32 v75, 0xffff0000, v91
	v_pk_mul_f32 v[72:73], v[76:77], v[72:73] op_sel_hi:[0,1]
	v_pk_mul_f32 v[74:75], v[76:77], v[74:75] op_sel_hi:[0,1]
	v_pk_mul_f32 v[84:85], v[4:5], v[72:73]
	v_pk_mul_f32 v[86:87], v[6:7], v[74:75]
	global_store_dwordx4 v41, v[84:87], s[14:15] offset:1024
	s_nop 0
	v_lshlrev_b32_e32 v72, 16, v92
	v_and_b32_e32 v73, 0xffff0000, v92
	v_lshlrev_b32_e32 v74, 16, v93
	v_and_b32_e32 v75, 0xffff0000, v93
	v_pk_mul_f32 v[72:73], v[76:77], v[72:73] op_sel_hi:[0,1]
	v_pk_mul_f32 v[74:75], v[76:77], v[74:75] op_sel_hi:[0,1]
	v_pk_mul_f32 v[80:81], v[8:9], v[72:73]
	v_pk_mul_f32 v[82:83], v[10:11], v[74:75]
	global_store_dwordx4 v41, v[80:83], s[14:15] offset:2048
	s_nop 0
	v_lshlrev_b32_e32 v72, 16, v94
	v_and_b32_e32 v73, 0xffff0000, v94
	v_lshlrev_b32_e32 v74, 16, v95
	v_and_b32_e32 v75, 0xffff0000, v95
	v_pk_mul_f32 v[72:73], v[76:77], v[72:73] op_sel_hi:[0,1]
	v_pk_mul_f32 v[74:75], v[76:77], v[74:75] op_sel_hi:[0,1]
	v_pk_mul_f32 v[84:85], v[12:13], v[72:73]
	v_pk_mul_f32 v[86:87], v[14:15], v[74:75]
	global_store_dwordx4 v41, v[84:87], s[14:15] offset:3072
	s_nop 0
	s_waitcnt vmcnt(16)
; __device__ __forceinline__ float bflo(unsigned w) { return __uint_as_float(w << 16); }
; __device__ __forceinline__ float bfhi(unsigned w) { return __uint_as_float(w & 0xffff0000u); }
; __global__ void __launch_bounds__(512, 2) fwd_mega(Args a) {
;     ...
;         for (int row = gw; row < M; row += NGW) {
;             const float rs = row_rstd(ssf, row);
;             f32x4* orow = (f32x4*)(a.out + (size_t)row * D) + lane; const u32x2* xr = (const u32x2*)(XB + (size_t)row * D) + lane;
; #pragma unroll
;             for (int j = 0; j < 4; ++j) { const u32x2 w = xr[64 * j]; orow[64 * j] = (f32x4){bflo(w.x), bfhi(w.x), bflo(w.y), bfhi(w.y)} * rs * gv[j]; }
	v_pk_add_f32 v[96:97], v[96:97], v[100:101]
	v_pk_add_f32 v[98:99], v[98:99], v[102:103]
	v_pk_add_f32 v[104:105], v[104:105], v[108:109]
	v_pk_add_f32 v[106:107], v[106:107], v[110:111]
	v_pk_add_f32 v[96:97], v[96:97], v[104:105]
	v_pk_add_f32 v[98:99], v[98:99], v[106:107]
	v_add_f32_e32 v96, v96, v97
	v_add_f32_e32 v98, v98, v99
	v_add_f32_e32 v96, v96, v98
	v_fmamk_f32 v96, v96, 0x3a800000, v22
	v_mul_f32_e32 v97, 0x4b800000, v96
	v_cmp_gt_f32_e32 vcc, s1, v96
	s_nop 1
	v_cndmask_b32_e32 v96, v96, v97, vcc
	v_rsq_f32_e32 v96, v96
	s_nop 0
	v_mul_f32_e32 v97, 0x45800000, v96
	v_cndmask_b32_e32 v100, v96, v97, vcc
	s_lshl_b32 s14, s22, 12
	s_add_u32 s14, s50, s14
	s_addc_u32 s15, s51, 0
	v_lshlrev_b32_e32 v96, 16, v112
	v_and_b32_e32 v97, 0xffff0000, v112
	v_lshlrev_b32_e32 v98, 16, v113
	v_and_b32_e32 v99, 0xffff0000, v113
	v_pk_mul_f32 v[96:97], v[100:101], v[96:97] op_sel_hi:[0,1]
	v_pk_mul_f32 v[98:99], v[100:101], v[98:99] op_sel_hi:[0,1]
	v_pk_mul_f32 v[104:105], v[0:1], v[96:97]
	v_pk_mul_f32 v[106:107], v[2:3], v[98:99]
	global_store_dwordx4 v41, v[104:107], s[14:15]
	v_lshlrev_b32_e32 v96, 16, v114
	v_and_b32_e32 v97, 0xffff0000, v114
	v_lshlrev_b32_e32 v98, 16, v115
	v_and_b32_e32 v99, 0xffff0000, v115
	v_pk_mul_f32 v[96:97], v[100:101], v[96:97] op_sel_hi:[0,1]
	v_pk_mul_f32 v[98:99], v[100:101], v[98:99] op_sel_hi:[0,1]
	v_pk_mul_f32 v[108:109], v[4:5], v[96:97]
	v_pk_mul_f32 v[110:111], v[6:7], v[98:99]
	global_store_dwordx4 v41, v[108:111], s[14:15] offset:1024
	s_nop 0
	v_lshlrev_b32_e32 v96, 16, v116
	v_and_b32_e32 v97, 0xffff0000, v116
	v_lshlrev_b32_e32 v98, 16, v117
	v_and_b32_e32 v99, 0xffff0000, v117
	v_pk_mul_f32 v[96:97], v[100:101], v[96:97] op_sel_hi:[0,1]
	v_pk_mul_f32 v[98:99], v[100:101], v[98:99] op_sel_hi:[0,1]
	v_pk_mul_f32 v[104:105], v[8:9], v[96:97]
	v_pk_mul_f32 v[106:107], v[10:11], v[98:99]
	global_store_dwordx4 v41, v[104:107], s[14:15] offset:2048
	s_nop 0
	v_lshlrev_b32_e32 v96, 16, v118
	v_and_b32_e32 v97, 0xffff0000, v118
	v_lshlrev_b32_e32 v98, 16, v119
	v_and_b32_e32 v99, 0xffff0000, v119
	v_pk_mul_f32 v[96:97], v[100:101], v[96:97] op_sel_hi:[0,1]
	v_pk_mul_f32 v[98:99], v[100:101], v[98:99] op_sel_hi:[0,1]
	v_pk_mul_f32 v[108:109], v[12:13], v[96:97]
	v_pk_mul_f32 v[110:111], v[14:15], v[98:99]
	global_store_dwordx4 v41, v[108:111], s[14:15] offset:3072
	s_nop 0
	s_waitcnt vmcnt(12)
	v_pk_add_f32 v[120:121], v[120:121], v[124:125]
	v_pk_add_f32 v[122:123], v[122:123], v[126:127]
	v_pk_add_f32 v[128:129], v[128:129], v[132:133]
	v_pk_add_f32 v[130:131], v[130:131], v[134:135]
	v_pk_add_f32 v[120:121], v[120:121], v[128:129]
	v_pk_add_f32 v[122:123], v[122:123], v[130:131]
	v_add_f32_e32 v120, v120, v121
	v_add_f32_e32 v122, v122, v123
	v_add_f32_e32 v120, v120, v122
	v_fmamk_f32 v120, v120, 0x3a800000, v22
	v_mul_f32_e32 v121, 0x4b800000, v120
	v_cmp_gt_f32_e32 vcc, s1, v120
	s_nop 1
	v_cndmask_b32_e32 v120, v120, v121, vcc
	v_rsq_f32_e32 v120, v120
	s_nop 0
	v_mul_f32_e32 v121, 0x45800000, v120
	v_cndmask_b32_e32 v124, v120, v121, vcc
	s_lshl_b32 s14, s23, 12
	s_add_u32 s14, s50, s14
	s_addc_u32 s15, s51, 0
	v_lshlrev_b32_e32 v120, 16, v136
	v_and_b32_e32 v121, 0xffff0000, v136
	v_lshlrev_b32_e32 v122, 16, v137
	v_and_b32_e32 v123, 0xffff0000, v137
	v_pk_mul_f32 v[120:121], v[124:125], v[120:121] op_sel_hi:[0,1]
	v_pk_mul_f32 v[122:123], v[124:125], v[122:123] op_sel_hi:[0,1]
	v_pk_mul_f32 v[128:129], v[0:1], v[120:121]
	v_pk_mul_f32 v[130:131], v[2:3], v[122:123]
	global_store_dwordx4 v41, v[128:131], s[14:15]
	v_lshlrev_b32_e32 v120, 16, v138
	v_and_b32_e32 v121, 0xffff0000, v138
	v_lshlrev_b32_e32 v122, 16, v139
	v_and_b32_e32 v123, 0xffff0000, v139
	v_pk_mul_f32 v[120:121], v[124:125], v[120:121] op_sel_hi:[0,1]
	v_pk_mul_f32 v[122:123], v[124:125], v[122:123] op_sel_hi:[0,1]
	v_pk_mul_f32 v[132:133], v[4:5], v[120:121]
	v_pk_mul_f32 v[134:135], v[6:7], v[122:123]
	global_store_dwordx4 v41, v[132:135], s[14:15] offset:1024
	s_nop 0
	v_lshlrev_b32_e32 v120, 16, v140
	v_and_b32_e32 v121, 0xffff0000, v140
	v_lshlrev_b32_e32 v122, 16, v141
	v_and_b32_e32 v123, 0xffff0000, v141
	v_pk_mul_f32 v[120:121], v[124:125], v[120:121] op_sel_hi:[0,1]
	v_pk_mul_f32 v[122:123], v[124:125], v[122:123] op_sel_hi:[0,1]
	v_pk_mul_f32 v[128:129], v[8:9], v[120:121]
	v_pk_mul_f32 v[130:131], v[10:11], v[122:123]
	global_store_dwordx4 v41, v[128:131], s[14:15] offset:2048
	s_nop 0
	v_lshlrev_b32_e32 v120, 16, v142
	v_and_b32_e32 v121, 0xffff0000, v142
	v_lshlrev_b32_e32 v122, 16, v143
	v_and_b32_e32 v123, 0xffff0000, v143
	v_pk_mul_f32 v[120:121], v[124:125], v[120:121] op_sel_hi:[0,1]
	v_pk_mul_f32 v[122:123], v[124:125], v[122:123] op_sel_hi:[0,1]
	v_pk_mul_f32 v[132:133], v[12:13], v[120:121]
	v_pk_mul_f32 v[134:135], v[14:15], v[122:123]
	global_store_dwordx4 v41, v[132:135], s[14:15] offset:3072
	s_nop 0
	s_mul_i32 s12, s16, 4
	s_add_i32 s0, s0, s12
	s_cmpk_gt_i32 s0, 0x3fff
	s_cbranch_scc0 .Lfn_loop
